# ResNorm part 1: residual tile fetched with full-line LDS-DMA loads into a per-wave LDS ring and read back in accumulator layout
# speedup vs baseline: 1.0189x; 1.0027x over previous
.LBB0_832:
	s_lshr_b32 s26, s26, 2
	s_mulk_i32 s26, 0x1800
	s_lshl_b32 s38, s35, 5
	s_addk_i32 s26, 0x1800
	s_and_b64 s[2:3], s[2:3], exec
	s_cselect_b32 s26, 0, s26
	s_lshl_b32 s2, s62, 8
	s_or_b32 s2, s2, s38
	v_lshrrev_b32_e32 v128, 2, v192
	v_and_or_b32 v210, v128, 12, s2
	s_lshl_b64 s[2:3], s[26:27], 2
	v_readlane_b32 s38, v255, 12
	v_ashrrev_i32_e32 v161, 31, v160
	v_readlane_b32 s39, v255, 13
	s_add_u32 s38, s38, s2
	v_ashrrev_i32_e32 v211, 31, v210
	v_lshlrev_b64 v[130:131], 10, v[160:161]
	s_addc_u32 s39, s39, s3
	v_lshl_add_u64 v[206:207], v[130:131], 0, v[210:211]
	v_lshl_add_u64 v[128:129], v[210:211], 2, s[38:39]
	v_lshlrev_b64 v[150:151], 2, v[206:207]
	global_load_dwordx4 v[140:143], v[128:129], off
	global_load_dwordx4 v[136:139], v[128:129], off offset:64
	global_load_dwordx4 v[132:135], v[128:129], off offset:512
	s_nop 0
	global_load_dwordx4 v[128:131], v[128:129], off offset:576
	s_add_u32 s36, s76, s36
	v_cndmask_b32_e64 v152, 0, 1, s[20:21]
	s_addc_u32 s37, s77, s37
	v_readlane_b32 s52, v254, 49
	v_cmp_ne_u32_e64 s[38:39], 1, v152
	v_readlane_b32 s53, v254, 50
	v_readlane_b32 s20, v255, 16
	v_readlane_b32 s21, v255, 17
	s_lshl_b32 s26, s35, 2
	v_cmp_gt_u32_e64 s[40:41], 16, v224
	s_add_i32 s26, s26, 0
	s_movk_i32 s42, 0x210
	v_lshrrev_b32_e32 v251, 3, v219
	v_and_b32_e32 v193, 7, v219
	v_xor_b32_e32 v193, v193, v251
	v_and_b32_e32 v212, 0xc0, v160
	v_add_u32_e32 v212, v212, v251
	v_lshlrev_b32_e32 v212, 12, v212
	v_lshl_or_b32 v212, v193, 4, v212
	v_and_b32_e32 v251, 0xfffffff3, v210
	v_lshl_add_u32 v212, v251, 2, v212
	s_mul_i32 s101, s33, 192
	s_add_i32 s101, s101, 0x4000
	v_and_b32_e32 v251, 15, v219
	v_lshrrev_b32_e32 v193, 4, v219
	v_and_b32_e32 v213, 7, v251
	v_xor_b32_e32 v193, v193, v213
	v_lshlrev_b32_e32 v213, 7, v251
	v_add_u32_e32 v213, s101, v213
	v_xor_b32_e32 v250, 4, v193
	v_lshl_add_u32 v250, v250, 4, v213
	v_lshl_add_u32 v213, v193, 4, v213
	s_add_u32 s98, s0, 0x0
	s_addc_u32 s99, s1, 0
	s_add_i32 m0, s101, 0x0
	s_nop 0
	global_load_lds_dwordx4 v212, s[98:99]
	s_add_u32 s98, s0, 0x8000
	s_addc_u32 s99, s1, 0
	s_add_i32 m0, s101, 0x400
	s_nop 0
	global_load_lds_dwordx4 v212, s[98:99]
	s_add_u32 s98, s0, 0x200
	s_addc_u32 s99, s1, 0
	s_add_i32 m0, s101, 0x800
	s_nop 0
	global_load_lds_dwordx4 v212, s[98:99]
	s_add_u32 s98, s0, 0x8200
	s_addc_u32 s99, s1, 0
	s_add_i32 m0, s101, 0xc00
	s_nop 0
	global_load_lds_dwordx4 v212, s[98:99]
	v_lshl_add_u64 v[208:209], s[36:37], 0, v[150:151]
	v_or_b32_e32 v184, 16, v160
	v_ashrrev_i32_e32 v185, 31, v184
	v_lshlrev_b64 v[226:227], 10, v[184:185]
	v_lshl_add_u64 v[202:203], v[226:227], 0, v[210:211]
	v_lshlrev_b64 v[226:227], 2, v[202:203]
	v_lshl_add_u64 v[204:205], s[36:37], 0, v[226:227]
	s_add_u32 s98, s0, 0x10000
	s_addc_u32 s99, s1, 0
	s_add_i32 m0, s101, 0x1000
	s_nop 0
	global_load_lds_dwordx4 v212, s[98:99]
	s_add_u32 s98, s0, 0x18000
	s_addc_u32 s99, s1, 0
	s_add_i32 m0, s101, 0x1400
	s_nop 0
	global_load_lds_dwordx4 v212, s[98:99]
	s_add_u32 s98, s0, 0x10200
	s_addc_u32 s99, s1, 0
	s_add_i32 m0, s101, 0x1800
	s_nop 0
	global_load_lds_dwordx4 v212, s[98:99]
	s_add_u32 s98, s0, 0x18200
	s_addc_u32 s99, s1, 0
	s_add_i32 m0, s101, 0x1c00
	s_nop 0
	global_load_lds_dwordx4 v212, s[98:99]
	v_or_b32_e32 v184, 32, v160
	v_ashrrev_i32_e32 v185, 31, v184
	v_lshlrev_b64 v[226:227], 10, v[184:185]
	v_lshl_add_u64 v[198:199], v[226:227], 0, v[210:211]
	v_lshlrev_b64 v[226:227], 2, v[198:199]
	v_lshl_add_u64 v[200:201], s[36:37], 0, v[226:227]
	s_add_u32 s98, s0, 0x20000
	s_addc_u32 s99, s1, 0
	s_add_i32 m0, s101, 0x2000
	s_nop 0
	global_load_lds_dwordx4 v212, s[98:99]
	s_add_u32 s98, s0, 0x28000
	s_addc_u32 s99, s1, 0
	s_add_i32 m0, s101, 0x2400
	s_nop 0
	global_load_lds_dwordx4 v212, s[98:99]
	s_add_u32 s98, s0, 0x20200
	s_addc_u32 s99, s1, 0
	s_add_i32 m0, s101, 0x2800
	s_nop 0
	global_load_lds_dwordx4 v212, s[98:99]
	s_add_u32 s98, s0, 0x28200
	s_addc_u32 s99, s1, 0
	s_add_i32 m0, s101, 0x2c00
	s_nop 0
	global_load_lds_dwordx4 v212, s[98:99]
	v_or_b32_e32 v184, 48, v160
	v_ashrrev_i32_e32 v185, 31, v184
	v_lshlrev_b64 v[226:227], 10, v[184:185]
	v_lshl_add_u64 v[194:195], v[226:227], 0, v[210:211]
	v_lshlrev_b64 v[226:227], 2, v[194:195]
	v_lshl_add_u64 v[196:197], s[36:37], 0, v[226:227]
	v_add_u32_e32 v184, 0x80, v160
	v_ashrrev_i32_e32 v185, 31, v184
	v_lshlrev_b64 v[226:227], 10, v[184:185]
	v_lshl_add_u64 v[174:175], v[226:227], 0, v[210:211]
	v_lshlrev_b64 v[226:227], 2, v[174:175]
	v_lshl_add_u64 v[176:177], s[36:37], 0, v[226:227]
	v_add_u32_e32 v184, 0x90, v160
	v_ashrrev_i32_e32 v185, 31, v184
	v_lshlrev_b64 v[226:227], 10, v[184:185]
	v_lshl_add_u64 v[170:171], v[226:227], 0, v[210:211]
	v_lshlrev_b64 v[226:227], 2, v[170:171]
	v_lshl_add_u64 v[172:173], s[36:37], 0, v[226:227]
	v_add_u32_e32 v184, 0xa0, v160
	v_ashrrev_i32_e32 v185, 31, v184
	v_lshlrev_b64 v[226:227], 10, v[184:185]
	v_lshl_add_u64 v[166:167], v[226:227], 0, v[210:211]
	v_lshlrev_b64 v[226:227], 2, v[166:167]
	v_lshl_add_u64 v[168:169], s[36:37], 0, v[226:227]
	v_add_u32_e32 v184, 0xb0, v160
	v_ashrrev_i32_e32 v185, 31, v184
	v_lshlrev_b64 v[226:227], 10, v[184:185]
	v_lshl_add_u64 v[162:163], v[226:227], 0, v[210:211]
	v_lshlrev_b64 v[226:227], 2, v[162:163]
	v_lshl_add_u64 v[164:165], s[36:37], 0, v[226:227]
	s_waitcnt vmcnt(8)
	ds_read_b128 v[226:229], v213 offset:0
	ds_read_b128 v[230:233], v250 offset:0
	ds_read_b128 v[234:237], v213 offset:2048
	ds_read_b128 v[238:241], v250 offset:2048
	s_waitcnt lgkmcnt(0)
	s_add_u32 s98, s0, 0x30000
	s_addc_u32 s99, s1, 0
	s_add_i32 m0, s101, 0x0
	s_nop 0
	global_load_lds_dwordx4 v212, s[98:99]
	s_add_u32 s98, s0, 0x38000
	s_addc_u32 s99, s1, 0
	s_add_i32 m0, s101, 0x400
	s_nop 0
	global_load_lds_dwordx4 v212, s[98:99]
	s_add_u32 s98, s0, 0x30200
	s_addc_u32 s99, s1, 0
	s_add_i32 m0, s101, 0x800
	s_nop 0
	global_load_lds_dwordx4 v212, s[98:99]
	s_add_u32 s98, s0, 0x38200
	s_addc_u32 s99, s1, 0
	s_add_i32 m0, s101, 0xc00
	s_nop 0
	global_load_lds_dwordx4 v212, s[98:99]
	v_pk_fma_f32 v[158:159], v[126:127], v[142:143], v[228:229]
	v_pk_fma_f32 v[156:157], v[124:125], v[140:141], v[226:227]
	v_pk_fma_f32 v[154:155], v[122:123], v[138:139], v[232:233]
	v_pk_fma_f32 v[152:153], v[120:121], v[136:137], v[230:231]
	v_pk_fma_f32 v[150:151], v[118:119], v[134:135], v[236:237]
	v_pk_fma_f32 v[148:149], v[116:117], v[132:133], v[234:235]
	v_pk_fma_f32 v[118:119], v[114:115], v[130:131], v[240:241]
	v_pk_fma_f32 v[116:117], v[112:113], v[128:129], v[238:239]
.Lrn_ns_0:
	v_and_b32_e32 v114, 64, v219
	v_xor_b32_e32 v113, 16, v219
	v_add_u32_e32 v114, 64, v114
	v_xor_b32_e32 v115, 32, v219
	v_cmp_lt_i32_e32 vcc, v113, v114
	s_nop 1
	v_cndmask_b32_e32 v113, v219, v113, vcc
	v_cmp_lt_i32_e32 vcc, v115, v114
	v_lshlrev_b32_e32 v120, 2, v113
	s_nop 0
	v_cndmask_b32_e32 v114, v219, v115, vcc
	v_lshlrev_b32_e32 v121, 2, v114
	v_mul_f32_e32 v186, v157, v157
	v_mul_f32_e32 v187, v159, v159
	v_fmac_f32_e32 v186, v156, v156
	v_fmac_f32_e32 v187, v158, v158
	v_add_f32_e32 v186, v186, v187
	v_mul_f32_e32 v187, v153, v153
	v_mul_f32_e32 v193, v155, v155
	v_fmac_f32_e32 v187, v152, v152
	v_fmac_f32_e32 v193, v154, v154
	v_add_f32_e32 v187, v187, v193
	v_add_f32_e32 v186, v186, v187
	v_mul_f32_e32 v187, v149, v149
	v_mul_f32_e32 v193, v151, v151
	v_fmac_f32_e32 v187, v148, v148
	v_fmac_f32_e32 v193, v150, v150
	v_add_f32_e32 v187, v187, v193
	v_add_f32_e32 v186, v186, v187
	v_mul_f32_e32 v187, v117, v117
	v_mul_f32_e32 v193, v119, v119
	v_fmac_f32_e32 v187, v116, v116
	v_fmac_f32_e32 v193, v118, v118
	v_add_f32_e32 v187, v187, v193
	v_add_f32_e32 v186, v186, v187
	ds_bpermute_b32 v225, v120, v186
	v_mov_b32_e32 v184, v160
	s_waitcnt lgkmcnt(0)
	v_add_f32_e32 v186, v186, v225
	ds_bpermute_b32 v225, v121, v186
	s_and_saveexec_b64 s[46:47], s[40:41]
	s_cbranch_execz .Lrn_nw_0
	v_lshl_add_u32 v187, v184, 4, s26
	s_waitcnt lgkmcnt(0)
	v_add_f32_e32 v186, v186, v225
	ds_write_b32 v187, v186
.Lrn_nw_0:
	s_or_b64 exec, exec, s[46:47]
	s_waitcnt lgkmcnt(0)
	s_waitcnt vmcnt(8)
	ds_read_b128 v[242:245], v213 offset:4096
	ds_read_b128 v[246:249], v250 offset:4096
	ds_read_b128 v[180:183], v213 offset:6144
	ds_read_b128 v[188:191], v250 offset:6144
	s_waitcnt lgkmcnt(0)
	s_add_u32 s98, s0, 0x80000
	s_addc_u32 s99, s1, 0
	s_add_i32 m0, s101, 0x1000
	s_nop 0
	global_load_lds_dwordx4 v212, s[98:99]
	s_add_u32 s98, s0, 0x88000
	s_addc_u32 s99, s1, 0
	s_add_i32 m0, s101, 0x1400
	s_nop 0
	global_load_lds_dwordx4 v212, s[98:99]
	s_add_u32 s98, s0, 0x80200
	s_addc_u32 s99, s1, 0
	s_add_i32 m0, s101, 0x1800
	s_nop 0
	global_load_lds_dwordx4 v212, s[98:99]
	s_add_u32 s98, s0, 0x88200
	s_addc_u32 s99, s1, 0
	s_add_i32 m0, s101, 0x1c00
	s_nop 0
	global_load_lds_dwordx4 v212, s[98:99]
	v_pk_fma_f32 v[146:147], v[110:111], v[142:143], v[244:245]
	v_pk_fma_f32 v[144:145], v[108:109], v[140:141], v[242:243]
	v_pk_fma_f32 v[126:127], v[106:107], v[138:139], v[248:249]
	v_pk_fma_f32 v[124:125], v[104:105], v[136:137], v[246:247]
	v_pk_fma_f32 v[106:107], v[102:103], v[134:135], v[182:183]
	v_pk_fma_f32 v[104:105], v[100:101], v[132:133], v[180:181]
	v_pk_fma_f32 v[94:95], v[94:95], v[130:131], v[190:191]
	v_pk_fma_f32 v[92:93], v[92:93], v[128:129], v[188:189]
.Lrn_ns_1:
	v_mul_f32_e32 v186, v145, v145
	v_mul_f32_e32 v187, v147, v147
	v_fmac_f32_e32 v186, v144, v144
	v_fmac_f32_e32 v187, v146, v146
	v_add_f32_e32 v186, v186, v187
	v_mul_f32_e32 v187, v125, v125
	v_mul_f32_e32 v193, v127, v127
	v_fmac_f32_e32 v187, v124, v124
	v_fmac_f32_e32 v193, v126, v126
	v_add_f32_e32 v187, v187, v193
	v_add_f32_e32 v186, v186, v187
	v_mul_f32_e32 v187, v105, v105
	v_mul_f32_e32 v193, v107, v107
	v_fmac_f32_e32 v187, v104, v104
	v_fmac_f32_e32 v193, v106, v106
	v_add_f32_e32 v187, v187, v193
	v_add_f32_e32 v186, v186, v187
	v_mul_f32_e32 v187, v93, v93
	v_mul_f32_e32 v193, v95, v95
	v_fmac_f32_e32 v187, v92, v92
	v_fmac_f32_e32 v193, v94, v94
	v_add_f32_e32 v187, v187, v193
	v_add_f32_e32 v186, v186, v187
	ds_bpermute_b32 v225, v120, v186
	v_or_b32_e32 v184, 16, v160
	s_waitcnt lgkmcnt(0)
	v_add_f32_e32 v186, v186, v225
	ds_bpermute_b32 v225, v121, v186
	s_and_saveexec_b64 s[46:47], s[40:41]
	s_cbranch_execz .Lrn_nw_1
	v_lshl_add_u32 v187, v184, 4, s26
	s_waitcnt lgkmcnt(0)
	v_add_f32_e32 v186, v186, v225
	ds_write_b32 v187, v186
.Lrn_nw_1:
	s_or_b64 exec, exec, s[46:47]
	s_waitcnt lgkmcnt(0)
	s_waitcnt vmcnt(8)
	ds_read_b128 v[226:229], v213 offset:8192
	ds_read_b128 v[230:233], v250 offset:8192
	ds_read_b128 v[234:237], v213 offset:10240
	ds_read_b128 v[238:241], v250 offset:10240
	s_waitcnt lgkmcnt(0)
	s_add_u32 s98, s0, 0x90000
	s_addc_u32 s99, s1, 0
	s_add_i32 m0, s101, 0x2000
	s_nop 0
	global_load_lds_dwordx4 v212, s[98:99]
	s_add_u32 s98, s0, 0x98000
	s_addc_u32 s99, s1, 0
	s_add_i32 m0, s101, 0x2400
	s_nop 0
	global_load_lds_dwordx4 v212, s[98:99]
	s_add_u32 s98, s0, 0x90200
	s_addc_u32 s99, s1, 0
	s_add_i32 m0, s101, 0x2800
	s_nop 0
	global_load_lds_dwordx4 v212, s[98:99]
	s_add_u32 s98, s0, 0x98200
	s_addc_u32 s99, s1, 0
	s_add_i32 m0, s101, 0x2c00
	s_nop 0
	global_load_lds_dwordx4 v212, s[98:99]
	v_pk_fma_f32 v[98:99], v[98:99], v[142:143], v[228:229]
	v_pk_fma_f32 v[96:97], v[96:97], v[140:141], v[226:227]
	v_pk_fma_f32 v[90:91], v[90:91], v[138:139], v[232:233]
	v_pk_fma_f32 v[88:89], v[88:89], v[136:137], v[230:231]
	v_pk_fma_f32 v[86:87], v[86:87], v[134:135], v[236:237]
	v_pk_fma_f32 v[84:85], v[84:85], v[132:133], v[234:235]
	v_pk_fma_f32 v[78:79], v[78:79], v[130:131], v[240:241]
	v_pk_fma_f32 v[76:77], v[76:77], v[128:129], v[238:239]
.Lrn_ns_2:
	v_mul_f32_e32 v186, v97, v97
	v_mul_f32_e32 v187, v99, v99
	v_fmac_f32_e32 v186, v96, v96
	v_fmac_f32_e32 v187, v98, v98
	v_add_f32_e32 v186, v186, v187
	v_mul_f32_e32 v187, v89, v89
	v_mul_f32_e32 v193, v91, v91
	v_fmac_f32_e32 v187, v88, v88
	v_fmac_f32_e32 v193, v90, v90
	v_add_f32_e32 v187, v187, v193
	v_add_f32_e32 v186, v186, v187
	v_mul_f32_e32 v187, v85, v85
	v_mul_f32_e32 v193, v87, v87
	v_fmac_f32_e32 v187, v84, v84
	v_fmac_f32_e32 v193, v86, v86
	v_add_f32_e32 v187, v187, v193
	v_add_f32_e32 v186, v186, v187
	v_mul_f32_e32 v187, v77, v77
	v_mul_f32_e32 v193, v79, v79
	v_fmac_f32_e32 v187, v76, v76
	v_fmac_f32_e32 v193, v78, v78
	v_add_f32_e32 v187, v187, v193
	v_add_f32_e32 v186, v186, v187
	ds_bpermute_b32 v225, v120, v186
	v_or_b32_e32 v184, 32, v160
	s_waitcnt lgkmcnt(0)
	v_add_f32_e32 v186, v186, v225
	ds_bpermute_b32 v225, v121, v186
	s_and_saveexec_b64 s[46:47], s[40:41]
	s_cbranch_execz .Lrn_nw_2
	v_lshl_add_u32 v187, v184, 4, s26
	s_waitcnt lgkmcnt(0)
	v_add_f32_e32 v186, v186, v225
	ds_write_b32 v187, v186
.Lrn_nw_2:
	s_or_b64 exec, exec, s[46:47]
	s_waitcnt lgkmcnt(0)
	s_waitcnt vmcnt(8)
	ds_read_b128 v[242:245], v213 offset:0
	ds_read_b128 v[246:249], v250 offset:0
	ds_read_b128 v[180:183], v213 offset:2048
	ds_read_b128 v[188:191], v250 offset:2048
	s_waitcnt lgkmcnt(0)
	s_add_u32 s98, s0, 0xa0000
	s_addc_u32 s99, s1, 0
	s_add_i32 m0, s101, 0x0
	s_nop 0
	global_load_lds_dwordx4 v212, s[98:99]
	s_add_u32 s98, s0, 0xa8000
	s_addc_u32 s99, s1, 0
	s_add_i32 m0, s101, 0x400
	s_nop 0
	global_load_lds_dwordx4 v212, s[98:99]
	s_add_u32 s98, s0, 0xa0200
	s_addc_u32 s99, s1, 0
	s_add_i32 m0, s101, 0x800
	s_nop 0
	global_load_lds_dwordx4 v212, s[98:99]
	s_add_u32 s98, s0, 0xa8200
	s_addc_u32 s99, s1, 0
	s_add_i32 m0, s101, 0xc00
	s_nop 0
	global_load_lds_dwordx4 v212, s[98:99]
	v_pk_fma_f32 v[82:83], v[82:83], v[142:143], v[244:245]
	v_pk_fma_f32 v[80:81], v[80:81], v[140:141], v[242:243]
	v_pk_fma_f32 v[74:75], v[74:75], v[138:139], v[248:249]
	v_pk_fma_f32 v[72:73], v[72:73], v[136:137], v[246:247]
	v_pk_fma_f32 v[70:71], v[70:71], v[134:135], v[182:183]
	v_pk_fma_f32 v[68:69], v[68:69], v[132:133], v[180:181]
	v_pk_fma_f32 v[62:63], v[62:63], v[130:131], v[190:191]
	v_pk_fma_f32 v[60:61], v[60:61], v[128:129], v[188:189]
.Lrn_ns_3:
	v_mul_f32_e32 v186, v81, v81
	v_mul_f32_e32 v187, v83, v83
	v_fmac_f32_e32 v186, v80, v80
	v_fmac_f32_e32 v187, v82, v82
	v_add_f32_e32 v186, v186, v187
	v_mul_f32_e32 v187, v73, v73
	v_mul_f32_e32 v193, v75, v75
	v_fmac_f32_e32 v187, v72, v72
	v_fmac_f32_e32 v193, v74, v74
	v_add_f32_e32 v187, v187, v193
	v_add_f32_e32 v186, v186, v187
	v_mul_f32_e32 v187, v69, v69
	v_mul_f32_e32 v193, v71, v71
	v_fmac_f32_e32 v187, v68, v68
	v_fmac_f32_e32 v193, v70, v70
	v_add_f32_e32 v187, v187, v193
	v_add_f32_e32 v186, v186, v187
	v_mul_f32_e32 v187, v61, v61
	v_mul_f32_e32 v193, v63, v63
	v_fmac_f32_e32 v187, v60, v60
	v_fmac_f32_e32 v193, v62, v62
	v_add_f32_e32 v187, v187, v193
	v_add_f32_e32 v186, v186, v187
	ds_bpermute_b32 v225, v120, v186
	v_or_b32_e32 v184, 48, v160
	s_waitcnt lgkmcnt(0)
	v_add_f32_e32 v186, v186, v225
	ds_bpermute_b32 v225, v121, v186
	s_and_saveexec_b64 s[46:47], s[40:41]
	s_cbranch_execz .Lrn_nw_3
	v_lshl_add_u32 v187, v184, 4, s26
	s_waitcnt lgkmcnt(0)
	v_add_f32_e32 v186, v186, v225
	ds_write_b32 v187, v186
.Lrn_nw_3:
	s_or_b64 exec, exec, s[46:47]
	s_waitcnt lgkmcnt(0)
	s_waitcnt vmcnt(8)
	ds_read_b128 v[226:229], v213 offset:4096
	ds_read_b128 v[230:233], v250 offset:4096
	ds_read_b128 v[234:237], v213 offset:6144
	ds_read_b128 v[238:241], v250 offset:6144
	s_waitcnt lgkmcnt(0)
	s_add_u32 s98, s0, 0xb0000
	s_addc_u32 s99, s1, 0
	s_add_i32 m0, s101, 0x1000
	s_nop 0
	global_load_lds_dwordx4 v212, s[98:99]
	s_add_u32 s98, s0, 0xb8000
	s_addc_u32 s99, s1, 0
	s_add_i32 m0, s101, 0x1400
	s_nop 0
	global_load_lds_dwordx4 v212, s[98:99]
	s_add_u32 s98, s0, 0xb0200
	s_addc_u32 s99, s1, 0
	s_add_i32 m0, s101, 0x1800
	s_nop 0
	global_load_lds_dwordx4 v212, s[98:99]
	s_add_u32 s98, s0, 0xb8200
	s_addc_u32 s99, s1, 0
	s_add_i32 m0, s101, 0x1c00
	s_nop 0
	global_load_lds_dwordx4 v212, s[98:99]
	v_pk_fma_f32 v[66:67], v[66:67], v[142:143], v[228:229]
	v_pk_fma_f32 v[64:65], v[64:65], v[140:141], v[226:227]
	v_pk_fma_f32 v[58:59], v[58:59], v[138:139], v[232:233]
	v_pk_fma_f32 v[56:57], v[56:57], v[136:137], v[230:231]
	v_pk_fma_f32 v[54:55], v[54:55], v[134:135], v[236:237]
	v_pk_fma_f32 v[52:53], v[52:53], v[132:133], v[234:235]
	v_pk_fma_f32 v[46:47], v[46:47], v[130:131], v[240:241]
	v_pk_fma_f32 v[44:45], v[44:45], v[128:129], v[238:239]
.Lrn_ns_4:
	v_mul_f32_e32 v186, v65, v65
	v_mul_f32_e32 v187, v67, v67
	v_fmac_f32_e32 v186, v64, v64
	v_fmac_f32_e32 v187, v66, v66
	v_add_f32_e32 v186, v186, v187
	v_mul_f32_e32 v187, v57, v57
	v_mul_f32_e32 v193, v59, v59
	v_fmac_f32_e32 v187, v56, v56
	v_fmac_f32_e32 v193, v58, v58
	v_add_f32_e32 v187, v187, v193
	v_add_f32_e32 v186, v186, v187
	v_mul_f32_e32 v187, v53, v53
	v_mul_f32_e32 v193, v55, v55
	v_fmac_f32_e32 v187, v52, v52
	v_fmac_f32_e32 v193, v54, v54
	v_add_f32_e32 v187, v187, v193
	v_add_f32_e32 v186, v186, v187
	v_mul_f32_e32 v187, v45, v45
	v_mul_f32_e32 v193, v47, v47
	v_fmac_f32_e32 v187, v44, v44
	v_fmac_f32_e32 v193, v46, v46
	v_add_f32_e32 v187, v187, v193
	v_add_f32_e32 v186, v186, v187
	ds_bpermute_b32 v225, v120, v186
	v_add_u32_e32 v184, 0x80, v160
	s_waitcnt lgkmcnt(0)
	v_add_f32_e32 v186, v186, v225
	ds_bpermute_b32 v225, v121, v186
	s_and_saveexec_b64 s[46:47], s[40:41]
	s_cbranch_execz .Lrn_nw_4
	v_lshl_add_u32 v187, v184, 4, s26
	s_waitcnt lgkmcnt(0)
	v_add_f32_e32 v186, v186, v225
	ds_write_b32 v187, v186
.Lrn_nw_4:
	s_or_b64 exec, exec, s[46:47]
	s_waitcnt lgkmcnt(0)
	s_waitcnt vmcnt(8)
	ds_read_b128 v[242:245], v213 offset:8192
	ds_read_b128 v[246:249], v250 offset:8192
	ds_read_b128 v[180:183], v213 offset:10240
	ds_read_b128 v[188:191], v250 offset:10240
	s_waitcnt lgkmcnt(0)
	v_pk_fma_f32 v[50:51], v[50:51], v[142:143], v[244:245]
	v_pk_fma_f32 v[48:49], v[48:49], v[140:141], v[242:243]
	v_pk_fma_f32 v[42:43], v[42:43], v[138:139], v[248:249]
	v_pk_fma_f32 v[40:41], v[40:41], v[136:137], v[246:247]
	v_pk_fma_f32 v[38:39], v[38:39], v[134:135], v[182:183]
	v_pk_fma_f32 v[36:37], v[36:37], v[132:133], v[180:181]
	v_pk_fma_f32 v[34:35], v[34:35], v[130:131], v[190:191]
	v_pk_fma_f32 v[32:33], v[32:33], v[128:129], v[188:189]
.Lrn_ns_5:
	v_mul_f32_e32 v186, v49, v49
	v_mul_f32_e32 v187, v51, v51
	v_fmac_f32_e32 v186, v48, v48
	v_fmac_f32_e32 v187, v50, v50
	v_add_f32_e32 v186, v186, v187
	v_mul_f32_e32 v187, v41, v41
	v_mul_f32_e32 v193, v43, v43
	v_fmac_f32_e32 v187, v40, v40
	v_fmac_f32_e32 v193, v42, v42
	v_add_f32_e32 v187, v187, v193
	v_add_f32_e32 v186, v186, v187
	v_mul_f32_e32 v187, v37, v37
	v_mul_f32_e32 v193, v39, v39
	v_fmac_f32_e32 v187, v36, v36
	v_fmac_f32_e32 v193, v38, v38
	v_add_f32_e32 v187, v187, v193
	v_add_f32_e32 v186, v186, v187
	v_mul_f32_e32 v187, v33, v33
	v_mul_f32_e32 v193, v35, v35
	v_fmac_f32_e32 v187, v32, v32
	v_fmac_f32_e32 v193, v34, v34
	v_add_f32_e32 v187, v187, v193
	v_add_f32_e32 v186, v186, v187
	ds_bpermute_b32 v225, v120, v186
	v_add_u32_e32 v184, 0x90, v160
	s_waitcnt lgkmcnt(0)
	v_add_f32_e32 v186, v186, v225
	ds_bpermute_b32 v225, v121, v186
	s_and_saveexec_b64 s[46:47], s[40:41]
	s_cbranch_execz .Lrn_nw_5
	v_lshl_add_u32 v187, v184, 4, s26
	s_waitcnt lgkmcnt(0)
	v_add_f32_e32 v186, v186, v225
	ds_write_b32 v187, v186
.Lrn_nw_5:
	s_or_b64 exec, exec, s[46:47]
	s_waitcnt lgkmcnt(0)
	s_waitcnt vmcnt(4)
	ds_read_b128 v[226:229], v213 offset:0
	ds_read_b128 v[230:233], v250 offset:0
	ds_read_b128 v[234:237], v213 offset:2048
	ds_read_b128 v[238:241], v250 offset:2048
	s_waitcnt lgkmcnt(0)
	v_pk_fma_f32 v[30:31], v[30:31], v[142:143], v[228:229]
	v_pk_fma_f32 v[28:29], v[28:29], v[140:141], v[226:227]
	v_pk_fma_f32 v[26:27], v[26:27], v[138:139], v[232:233]
	v_pk_fma_f32 v[24:25], v[24:25], v[136:137], v[230:231]
	v_pk_fma_f32 v[22:23], v[22:23], v[134:135], v[236:237]
	v_pk_fma_f32 v[20:21], v[20:21], v[132:133], v[234:235]
	v_pk_fma_f32 v[18:19], v[18:19], v[130:131], v[240:241]
	v_pk_fma_f32 v[16:17], v[16:17], v[128:129], v[238:239]

.Lrn_nw_6:
	s_or_b64 exec, exec, s[46:47]
	s_waitcnt lgkmcnt(0)
	s_waitcnt vmcnt(0)
	ds_read_b128 v[242:245], v213 offset:4096
	ds_read_b128 v[246:249], v250 offset:4096
	ds_read_b128 v[180:183], v213 offset:6144
	ds_read_b128 v[188:191], v250 offset:6144
	s_waitcnt lgkmcnt(0)
	v_pk_fma_f32 v[14:15], v[14:15], v[142:143], v[244:245]
	v_pk_fma_f32 v[12:13], v[12:13], v[140:141], v[242:243]
	v_pk_fma_f32 v[10:11], v[10:11], v[138:139], v[248:249]
	v_pk_fma_f32 v[8:9], v[8:9], v[136:137], v[246:247]
	v_pk_fma_f32 v[6:7], v[6:7], v[134:135], v[182:183]
	v_pk_fma_f32 v[4:5], v[4:5], v[132:133], v[180:181]
	v_pk_fma_f32 v[2:3], v[2:3], v[130:131], v[190:191]
	v_pk_fma_f32 v[0:1], v[0:1], v[128:129], v[188:189]
